# pf4fu + P1/P5 unit-start waits relaxed: first two counted waits of each unit allow the previous epilogue's stores (16 / 8) to stay outstanding (they only need the older cross-unit prefetched tiles)
# baseline (speedup 1.0000x reference)
.LBB0_177:
	s_ashr_i32 s29, s28, 31
	s_lshl_b64 s[38:39], s[28:29], 19
	s_add_u32 s38, s84, s38
	s_addc_u32 s39, s85, s39
	s_and_b64 s[40:41], s[36:37], exec
	s_cselect_b32 s29, s39, s1
	s_cselect_b32 s62, s38, s0
	s_ashr_i32 s35, s34, 31
	s_lshl_b64 s[40:41], s[34:35], 19
	s_add_u32 s40, s16, s40
	s_addc_u32 s41, s17, s41
	s_and_b64 s[46:47], s[36:37], exec
	s_cselect_b32 s63, s41, s45
	s_cselect_b32 s64, s40, s44
	s_lshl_b32 s35, s30, 8
	s_add_u32 s65, s44, 0x100
	v_mov_b32_e32 v2, 0
	v_or_b32_e32 v134, s35, v172
	v_lshl_add_u64 v[130:131], s[0:1], 0, v[148:149]
	v_lshl_add_u64 v[132:133], s[0:1], 0, v[150:151]
	s_addc_u32 s66, s45, 0
	s_mov_b32 s67, -2
	s_mov_b64 s[30:31], 0
	s_waitcnt lgkmcnt(0)
	ds_read_b128 v[160:163], v240
	ds_read_b128 v[164:167], v240 offset:1024
	ds_read_b128 v[178:181], v240 offset:2048
	ds_read_b128 v[182:185], v240 offset:3072
	s_add_u32 s44, s0, s30
	ds_read_b128 v[186:189], v240 offset:16384
	ds_read_b128 v[190:193], v240 offset:17408
	ds_read_b128 v[194:197], v240 offset:18432
	ds_read_b128 v[198:201], v240 offset:19456
	s_addc_u32 s45, s1, s31
	s_add_u32 s44, s44, 0x100
	s_addc_u32 s45, s45, 0
	s_add_u32 s72, s65, s30
	s_addc_u32 s73, s66, s31
	s_cmpk_eq_i32 s30, 0x700
	s_cselect_b32 s47, s29, s45
	s_cselect_b32 s46, s62, s44
	s_cselect_b32 s45, s63, s73
	s_cselect_b32 s44, s64, s72
	s_add_u32 s90, s0, s30
	s_addc_u32 s91, s1, s31
	s_add_i32 m0, s43, 0xc000
	ds_read_b128 v[202:205], v176
	ds_read_b128 v[206:209], v176 offset:1024
	ds_read_b128 v[210:213], v176 offset:2048
	ds_read_b128 v[214:217], v176 offset:3072
	ds_read_b128 v[218:221], v176 offset:4096
	ds_read_b128 v[222:225], v176 offset:5120
	ds_read_b128 v[226:229], v176 offset:6144
	ds_read_b128 v[230:233], v176 offset:7168
	global_load_lds_dwordx4 v148, s[90:91]
	s_add_i32 m0, s43, 0xe000
	s_nop 0
	global_load_lds_dwordx4 v150, s[90:91]
	s_waitcnt vmcnt(18)
	s_waitcnt lgkmcnt(0)
	s_barrier
	s_setprio 1
	v_mfma_f32_16x16x32_bf16 v[126:129], v[160:163], v[202:205], 0
	v_mfma_f32_16x16x32_bf16 v[126:129], v[164:167], v[206:209], v[126:129]
	v_mfma_f32_16x16x32_bf16 v[122:125], v[178:181], v[202:205], 0
	v_mfma_f32_16x16x32_bf16 v[122:125], v[182:185], v[206:209], v[122:125]
	v_mfma_f32_16x16x32_bf16 v[106:109], v[178:181], v[210:213], 0
	v_mfma_f32_16x16x32_bf16 v[106:109], v[182:185], v[214:217], v[106:109]
	v_mfma_f32_16x16x32_bf16 v[110:113], v[160:163], v[210:213], 0
	v_mfma_f32_16x16x32_bf16 v[110:113], v[164:167], v[214:217], v[110:113]
	v_mfma_f32_16x16x32_bf16 v[94:97], v[160:163], v[218:221], 0
	v_mfma_f32_16x16x32_bf16 v[94:97], v[164:167], v[222:225], v[94:97]
	v_mfma_f32_16x16x32_bf16 v[90:93], v[178:181], v[218:221], 0
	v_mfma_f32_16x16x32_bf16 v[90:93], v[182:185], v[222:225], v[90:93]
	v_mfma_f32_16x16x32_bf16 v[74:77], v[178:181], v[226:229], 0
	v_mfma_f32_16x16x32_bf16 v[74:77], v[182:185], v[230:233], v[74:77]
	v_mfma_f32_16x16x32_bf16 v[78:81], v[160:163], v[226:229], 0
	v_mfma_f32_16x16x32_bf16 v[78:81], v[164:167], v[230:233], v[78:81]
	v_mfma_f32_16x16x32_bf16 v[118:121], v[186:189], v[202:205], 0
	v_mfma_f32_16x16x32_bf16 v[118:121], v[190:193], v[206:209], v[118:121]
	v_mfma_f32_16x16x32_bf16 v[114:117], v[194:197], v[202:205], 0
	v_mfma_f32_16x16x32_bf16 v[114:117], v[198:201], v[206:209], v[114:117]
	v_mfma_f32_16x16x32_bf16 v[98:101], v[194:197], v[210:213], 0
	v_mfma_f32_16x16x32_bf16 v[98:101], v[198:201], v[214:217], v[98:101]
	v_mfma_f32_16x16x32_bf16 v[102:105], v[186:189], v[210:213], 0
	v_mfma_f32_16x16x32_bf16 v[102:105], v[190:193], v[214:217], v[102:105]
	v_mfma_f32_16x16x32_bf16 v[86:89], v[186:189], v[218:221], 0
	v_mfma_f32_16x16x32_bf16 v[86:89], v[190:193], v[222:225], v[86:89]
	v_mfma_f32_16x16x32_bf16 v[82:85], v[194:197], v[218:221], 0
	v_mfma_f32_16x16x32_bf16 v[82:85], v[198:201], v[222:225], v[82:85]
	s_setprio 2
	s_barrier
	v_mfma_f32_16x16x32_bf16 v[66:69], v[194:197], v[226:229], 0
	v_mfma_f32_16x16x32_bf16 v[66:69], v[198:201], v[230:233], v[66:69]
	v_mfma_f32_16x16x32_bf16 v[70:73], v[186:189], v[226:229], 0
	v_mfma_f32_16x16x32_bf16 v[70:73], v[190:193], v[230:233], v[70:73]
	s_setprio 0
	s_nop 0
	s_add_i32 s72, s60, s33
	s_mov_b32 m0, s72
	ds_read_b128 v[202:205], v176 offset:16384
	ds_read_b128 v[206:209], v176 offset:17408
	ds_read_b128 v[210:213], v176 offset:18432
	ds_read_b128 v[214:217], v176 offset:19456
	ds_read_b128 v[218:221], v176 offset:20480
	ds_read_b128 v[222:225], v176 offset:21504
	ds_read_b128 v[226:229], v176 offset:22528
	ds_read_b128 v[230:233], v176 offset:23552
	global_load_lds_dwordx4 v140, s[44:45]
	s_add_i32 m0, s72, 0x2000
	s_add_u32 s72, s44, 0x40000
	s_addc_u32 s73, s45, 0
	s_add_i32 s74, s61, s33
	global_load_lds_dwordx4 v144, s[44:45]
	s_mov_b32 m0, s74
	s_add_u32 s94, s46, 0x80
	s_addc_u32 s95, s47, 0
	global_load_lds_dwordx4 v140, s[72:73]
	s_add_i32 m0, s74, 0x2000
	s_nop 0
	global_load_lds_dwordx4 v144, s[72:73]
	s_mov_b32 m0, s43
	s_nop 0
	global_load_lds_dwordx4 v138, s[46:47]
	s_mov_b32 m0, s54
	s_nop 0
	global_load_lds_dwordx4 v142, s[46:47]
	s_waitcnt vmcnt(24)
	s_waitcnt lgkmcnt(0)
	s_barrier
	s_setprio 1
	v_mfma_f32_16x16x32_bf16 v[62:65], v[160:163], v[202:205], 0
	v_mfma_f32_16x16x32_bf16 v[62:65], v[164:167], v[206:209], v[62:65]
	v_mfma_f32_16x16x32_bf16 v[58:61], v[178:181], v[202:205], 0
	v_mfma_f32_16x16x32_bf16 v[58:61], v[182:185], v[206:209], v[58:61]
	v_mfma_f32_16x16x32_bf16 v[42:45], v[178:181], v[210:213], 0
	v_mfma_f32_16x16x32_bf16 v[42:45], v[182:185], v[214:217], v[42:45]
	v_mfma_f32_16x16x32_bf16 v[46:49], v[160:163], v[210:213], 0
	v_mfma_f32_16x16x32_bf16 v[46:49], v[164:167], v[214:217], v[46:49]
	v_mfma_f32_16x16x32_bf16 v[30:33], v[160:163], v[218:221], 0
	v_mfma_f32_16x16x32_bf16 v[30:33], v[164:167], v[222:225], v[30:33]
	v_mfma_f32_16x16x32_bf16 v[26:29], v[178:181], v[218:221], 0
	v_mfma_f32_16x16x32_bf16 v[26:29], v[182:185], v[222:225], v[26:29]
	v_mfma_f32_16x16x32_bf16 v[10:13], v[178:181], v[226:229], 0
	v_mfma_f32_16x16x32_bf16 v[10:13], v[182:185], v[230:233], v[10:13]
	v_mfma_f32_16x16x32_bf16 v[14:17], v[160:163], v[226:229], 0
	v_mfma_f32_16x16x32_bf16 v[14:17], v[164:167], v[230:233], v[14:17]
	v_mfma_f32_16x16x32_bf16 v[54:57], v[186:189], v[202:205], 0
	v_mfma_f32_16x16x32_bf16 v[54:57], v[190:193], v[206:209], v[54:57]
	v_mfma_f32_16x16x32_bf16 v[50:53], v[194:197], v[202:205], 0
	v_mfma_f32_16x16x32_bf16 v[50:53], v[198:201], v[206:209], v[50:53]
	v_mfma_f32_16x16x32_bf16 v[34:37], v[194:197], v[210:213], 0
	v_mfma_f32_16x16x32_bf16 v[34:37], v[198:201], v[214:217], v[34:37]
	v_mfma_f32_16x16x32_bf16 v[38:41], v[186:189], v[210:213], 0
	v_mfma_f32_16x16x32_bf16 v[38:41], v[190:193], v[214:217], v[38:41]
	v_mfma_f32_16x16x32_bf16 v[22:25], v[186:189], v[218:221], 0
	v_mfma_f32_16x16x32_bf16 v[22:25], v[190:193], v[222:225], v[22:25]
	v_mfma_f32_16x16x32_bf16 v[18:21], v[194:197], v[218:221], 0
	v_mfma_f32_16x16x32_bf16 v[18:21], v[198:201], v[222:225], v[18:21]
	s_setprio 2
	s_barrier
	v_mfma_f32_16x16x32_bf16 v[2:5], v[194:197], v[226:229], 0
	v_mfma_f32_16x16x32_bf16 v[2:5], v[198:201], v[230:233], v[2:5]
	v_mfma_f32_16x16x32_bf16 v[6:9], v[186:189], v[226:229], 0
	v_mfma_f32_16x16x32_bf16 v[6:9], v[190:193], v[230:233], v[6:9]
	s_setprio 0
	s_nop 0
	s_add_i32 s72, 0, 0x18000
	s_add_i32 s73, 0, 0x1c000
	ds_read_b128 v[160:163], v240 offset:32768
	ds_read_b128 v[164:167], v240 offset:33792
	ds_read_b128 v[178:181], v240 offset:34816
	ds_read_b128 v[182:185], v240 offset:35840
	ds_read_b128 v[186:189], v240 offset:49152
	ds_read_b128 v[190:193], v240 offset:50176
	ds_read_b128 v[194:197], v240 offset:51200
	ds_read_b128 v[198:201], v240 offset:52224
	s_add_u32 s46, s46, 0x40000
	s_addc_u32 s47, s47, 0
	s_mov_b32 m0, s55
	ds_read_b128 v[202:205], v176 offset:32768
	ds_read_b128 v[206:209], v176 offset:33792
	ds_read_b128 v[210:213], v176 offset:34816
	ds_read_b128 v[214:217], v176 offset:35840
	ds_read_b128 v[218:221], v176 offset:36864
	ds_read_b128 v[222:225], v176 offset:37888
	ds_read_b128 v[226:229], v176 offset:38912
	ds_read_b128 v[230:233], v176 offset:39936
	global_load_lds_dwordx4 v138, s[46:47]
	s_mov_b32 m0, s56
	s_nop 0
	global_load_lds_dwordx4 v142, s[46:47]
	s_waitcnt vmcnt(8)
	s_waitcnt lgkmcnt(0)
	s_barrier
	s_setprio 1
	v_mfma_f32_16x16x32_bf16 v[126:129], v[160:163], v[202:205], v[126:129]
	v_mfma_f32_16x16x32_bf16 v[126:129], v[164:167], v[206:209], v[126:129]
	v_mfma_f32_16x16x32_bf16 v[122:125], v[178:181], v[202:205], v[122:125]
	v_mfma_f32_16x16x32_bf16 v[122:125], v[182:185], v[206:209], v[122:125]
	v_mfma_f32_16x16x32_bf16 v[106:109], v[178:181], v[210:213], v[106:109]
	v_mfma_f32_16x16x32_bf16 v[106:109], v[182:185], v[214:217], v[106:109]
	v_mfma_f32_16x16x32_bf16 v[110:113], v[160:163], v[210:213], v[110:113]
	v_mfma_f32_16x16x32_bf16 v[110:113], v[164:167], v[214:217], v[110:113]
	v_mfma_f32_16x16x32_bf16 v[94:97], v[160:163], v[218:221], v[94:97]
	v_mfma_f32_16x16x32_bf16 v[94:97], v[164:167], v[222:225], v[94:97]
	v_mfma_f32_16x16x32_bf16 v[90:93], v[178:181], v[218:221], v[90:93]
	v_mfma_f32_16x16x32_bf16 v[90:93], v[182:185], v[222:225], v[90:93]
	v_mfma_f32_16x16x32_bf16 v[74:77], v[178:181], v[226:229], v[74:77]
	v_mfma_f32_16x16x32_bf16 v[74:77], v[182:185], v[230:233], v[74:77]
	v_mfma_f32_16x16x32_bf16 v[78:81], v[160:163], v[226:229], v[78:81]
	v_mfma_f32_16x16x32_bf16 v[78:81], v[164:167], v[230:233], v[78:81]
	v_mfma_f32_16x16x32_bf16 v[118:121], v[186:189], v[202:205], v[118:121]
	v_mfma_f32_16x16x32_bf16 v[118:121], v[190:193], v[206:209], v[118:121]
	v_mfma_f32_16x16x32_bf16 v[114:117], v[194:197], v[202:205], v[114:117]
	v_mfma_f32_16x16x32_bf16 v[114:117], v[198:201], v[206:209], v[114:117]
	v_mfma_f32_16x16x32_bf16 v[98:101], v[194:197], v[210:213], v[98:101]
	v_mfma_f32_16x16x32_bf16 v[98:101], v[198:201], v[214:217], v[98:101]
	v_mfma_f32_16x16x32_bf16 v[102:105], v[186:189], v[210:213], v[102:105]
	v_mfma_f32_16x16x32_bf16 v[102:105], v[190:193], v[214:217], v[102:105]
	v_mfma_f32_16x16x32_bf16 v[86:89], v[186:189], v[218:221], v[86:89]
	v_mfma_f32_16x16x32_bf16 v[86:89], v[190:193], v[222:225], v[86:89]
	v_mfma_f32_16x16x32_bf16 v[82:85], v[194:197], v[218:221], v[82:85]
	v_mfma_f32_16x16x32_bf16 v[82:85], v[198:201], v[222:225], v[82:85]
	s_setprio 2
	s_barrier
	v_mfma_f32_16x16x32_bf16 v[66:69], v[194:197], v[226:229], v[66:69]
	v_mfma_f32_16x16x32_bf16 v[66:69], v[198:201], v[230:233], v[66:69]
	v_mfma_f32_16x16x32_bf16 v[70:73], v[186:189], v[226:229], v[70:73]
	v_mfma_f32_16x16x32_bf16 v[70:73], v[190:193], v[230:233], v[70:73]
	s_setprio 0
	s_nop 0
	s_add_i32 s46, s72, s33
	s_add_u32 s96, s44, 0x80
	s_addc_u32 s97, s45, 0
	s_mov_b32 m0, s46
	ds_read_b128 v[202:205], v176 offset:49152
	ds_read_b128 v[206:209], v176 offset:50176
	ds_read_b128 v[210:213], v176 offset:51200
	ds_read_b128 v[214:217], v176 offset:52224
	ds_read_b128 v[218:221], v176 offset:53248
	ds_read_b128 v[222:225], v176 offset:54272
	ds_read_b128 v[226:229], v176 offset:55296
	ds_read_b128 v[230:233], v176 offset:56320
	global_load_lds_dwordx4 v140, s[96:97]
	s_add_i32 m0, s46, 0x2000
	s_add_u32 s44, s44, 0x40080
	s_addc_u32 s45, s45, 0
	s_add_i32 s46, s73, s33
	global_load_lds_dwordx4 v144, s[96:97]
	s_mov_b32 m0, s46
	s_nop 0
	global_load_lds_dwordx4 v140, s[44:45]
	s_add_i32 m0, s46, 0x2000
	s_nop 0
	global_load_lds_dwordx4 v144, s[44:45]
	s_mov_b32 m0, s57
	s_nop 0
	global_load_lds_dwordx4 v138, s[94:95]
	s_mov_b32 m0, s58
	s_nop 0
	global_load_lds_dwordx4 v142, s[94:95]
	s_waitcnt vmcnt(8)
	s_waitcnt lgkmcnt(0)
	s_barrier
	s_setprio 1
	v_mfma_f32_16x16x32_bf16 v[62:65], v[160:163], v[202:205], v[62:65]
	v_mfma_f32_16x16x32_bf16 v[62:65], v[164:167], v[206:209], v[62:65]
	v_mfma_f32_16x16x32_bf16 v[58:61], v[178:181], v[202:205], v[58:61]
	v_mfma_f32_16x16x32_bf16 v[58:61], v[182:185], v[206:209], v[58:61]
	v_mfma_f32_16x16x32_bf16 v[42:45], v[178:181], v[210:213], v[42:45]
	v_mfma_f32_16x16x32_bf16 v[42:45], v[182:185], v[214:217], v[42:45]
	v_mfma_f32_16x16x32_bf16 v[46:49], v[160:163], v[210:213], v[46:49]
	v_mfma_f32_16x16x32_bf16 v[46:49], v[164:167], v[214:217], v[46:49]
	v_mfma_f32_16x16x32_bf16 v[30:33], v[160:163], v[218:221], v[30:33]
	v_mfma_f32_16x16x32_bf16 v[30:33], v[164:167], v[222:225], v[30:33]
	v_mfma_f32_16x16x32_bf16 v[26:29], v[178:181], v[218:221], v[26:29]
	v_mfma_f32_16x16x32_bf16 v[26:29], v[182:185], v[222:225], v[26:29]
	v_mfma_f32_16x16x32_bf16 v[10:13], v[178:181], v[226:229], v[10:13]
	v_mfma_f32_16x16x32_bf16 v[10:13], v[182:185], v[230:233], v[10:13]
	v_mfma_f32_16x16x32_bf16 v[14:17], v[160:163], v[226:229], v[14:17]
	v_mfma_f32_16x16x32_bf16 v[14:17], v[164:167], v[230:233], v[14:17]
	v_mfma_f32_16x16x32_bf16 v[54:57], v[186:189], v[202:205], v[54:57]
	v_mfma_f32_16x16x32_bf16 v[54:57], v[190:193], v[206:209], v[54:57]
	v_mfma_f32_16x16x32_bf16 v[50:53], v[194:197], v[202:205], v[50:53]
	v_mfma_f32_16x16x32_bf16 v[50:53], v[198:201], v[206:209], v[50:53]
	v_mfma_f32_16x16x32_bf16 v[34:37], v[194:197], v[210:213], v[34:37]
	v_mfma_f32_16x16x32_bf16 v[34:37], v[198:201], v[214:217], v[34:37]
	v_mfma_f32_16x16x32_bf16 v[38:41], v[186:189], v[210:213], v[38:41]
	v_mfma_f32_16x16x32_bf16 v[38:41], v[190:193], v[214:217], v[38:41]
	v_mfma_f32_16x16x32_bf16 v[22:25], v[186:189], v[218:221], v[22:25]
	v_mfma_f32_16x16x32_bf16 v[22:25], v[190:193], v[222:225], v[22:25]
	v_mfma_f32_16x16x32_bf16 v[18:21], v[194:197], v[218:221], v[18:21]
	v_mfma_f32_16x16x32_bf16 v[18:21], v[198:201], v[222:225], v[18:21]
	s_setprio 2
	s_barrier
	v_mfma_f32_16x16x32_bf16 v[2:5], v[194:197], v[226:229], v[2:5]
	v_mfma_f32_16x16x32_bf16 v[2:5], v[198:201], v[230:233], v[2:5]
	v_mfma_f32_16x16x32_bf16 v[6:9], v[186:189], v[226:229], v[6:9]
	v_mfma_f32_16x16x32_bf16 v[6:9], v[190:193], v[230:233], v[6:9]
	s_setprio 0
	s_nop 0
	s_add_i32 s67, s67, 2
	s_add_u32 s30, s30, 0x100
	s_addc_u32 s31, s31, 0
	s_cmp_gt_u32 s67, 13
	s_cbranch_scc1 .LBB0_181
	s_branch .LBB0_179

.LBB0_944:
	s_ashr_i32 s9, s8, 31
	s_lshl_b64 s[14:15], s[8:9], 19
	s_add_u32 s14, s64, s14
	s_addc_u32 s15, s65, s15
	s_and_b64 s[16:17], s[12:13], exec
	s_cselect_b32 s9, s15, s19
	s_cselect_b32 s39, s14, s18
	s_ashr_i32 s11, s10, 31
	s_lshl_b64 s[16:17], s[10:11], 19
	v_readlane_b32 s24, v245, 3
	v_readlane_b32 s25, v245, 4
	s_add_u32 s16, s24, s16
	s_addc_u32 s17, s25, s17
	s_and_b64 s[24:25], s[12:13], exec
	s_cselect_b32 s40, s17, s23
	s_cselect_b32 s41, s16, s22
	s_lshl_b32 s11, s20, 8
	s_add_u32 s42, s22, 0x100
	v_mov_b32_e32 v2, 0
	v_or_b32_e32 v146, s11, v228
	v_lshl_add_u64 v[142:143], s[18:19], 0, v[138:139]
	v_lshl_add_u64 v[144:145], s[18:19], 0, v[140:141]
	s_addc_u32 s43, s23, 0
	s_mov_b32 s44, -2
	s_mov_b64 s[20:21], 0
	ds_read_b128 v[154:157], v229
	ds_read_b128 v[158:161], v229 offset:1024
	ds_read_b128 v[162:165], v229 offset:2048
	ds_read_b128 v[166:169], v229 offset:3072
	s_add_u32 s22, s18, s20
	ds_read_b128 v[170:173], v229 offset:16384
	ds_read_b128 v[174:177], v229 offset:17408
	ds_read_b128 v[178:181], v229 offset:18432
	ds_read_b128 v[182:185], v229 offset:19456
	s_addc_u32 s23, s19, s21
	s_add_u32 s22, s22, 0x100
	s_addc_u32 s23, s23, 0
	s_add_u32 s45, s42, s20
	s_addc_u32 s46, s43, s21
	s_cmpk_eq_i32 s20, 0x700
	s_cselect_b32 s25, s9, s23
	s_cselect_b32 s24, s39, s22
	s_cselect_b32 s23, s40, s46
	s_cselect_b32 s22, s41, s45
	s_add_u32 s48, s18, s20
	s_addc_u32 s49, s19, s21
	s_add_i32 m0, s27, 0xc000
	ds_read_b128 v[186:189], v152
	ds_read_b128 v[190:193], v152 offset:1024
	ds_read_b128 v[194:197], v152 offset:2048
	ds_read_b128 v[198:201], v152 offset:3072
	ds_read_b128 v[202:205], v152 offset:4096
	ds_read_b128 v[206:209], v152 offset:5120
	ds_read_b128 v[210:213], v152 offset:6144
	ds_read_b128 v[214:217], v152 offset:7168
	global_load_lds_dwordx4 v138, s[48:49]
	s_add_i32 m0, s27, 0xe000
	s_nop 0
	global_load_lds_dwordx4 v140, s[48:49]
	s_waitcnt vmcnt(10)
	s_waitcnt lgkmcnt(0)
	s_barrier
	s_setprio 1
	v_mfma_f32_16x16x32_bf16 v[126:129], v[154:157], v[186:189], 0
	v_mfma_f32_16x16x32_bf16 v[126:129], v[158:161], v[190:193], v[126:129]
	v_mfma_f32_16x16x32_bf16 v[118:121], v[162:165], v[186:189], 0
	v_mfma_f32_16x16x32_bf16 v[118:121], v[166:169], v[190:193], v[118:121]
	v_mfma_f32_16x16x32_bf16 v[102:105], v[162:165], v[194:197], 0
	v_mfma_f32_16x16x32_bf16 v[102:105], v[166:169], v[198:201], v[102:105]
	v_mfma_f32_16x16x32_bf16 v[110:113], v[154:157], v[194:197], 0
	v_mfma_f32_16x16x32_bf16 v[110:113], v[158:161], v[198:201], v[110:113]
	v_mfma_f32_16x16x32_bf16 v[94:97], v[154:157], v[202:205], 0
	v_mfma_f32_16x16x32_bf16 v[94:97], v[158:161], v[206:209], v[94:97]
	v_mfma_f32_16x16x32_bf16 v[86:89], v[162:165], v[202:205], 0
	v_mfma_f32_16x16x32_bf16 v[86:89], v[166:169], v[206:209], v[86:89]
	v_mfma_f32_16x16x32_bf16 v[70:73], v[162:165], v[210:213], 0
	v_mfma_f32_16x16x32_bf16 v[70:73], v[166:169], v[214:217], v[70:73]
	v_mfma_f32_16x16x32_bf16 v[78:81], v[154:157], v[210:213], 0
	v_mfma_f32_16x16x32_bf16 v[78:81], v[158:161], v[214:217], v[78:81]
	v_mfma_f32_16x16x32_bf16 v[122:125], v[170:173], v[186:189], 0
	v_mfma_f32_16x16x32_bf16 v[122:125], v[174:177], v[190:193], v[122:125]
	v_mfma_f32_16x16x32_bf16 v[114:117], v[178:181], v[186:189], 0
	v_mfma_f32_16x16x32_bf16 v[114:117], v[182:185], v[190:193], v[114:117]
	v_mfma_f32_16x16x32_bf16 v[98:101], v[178:181], v[194:197], 0
	v_mfma_f32_16x16x32_bf16 v[98:101], v[182:185], v[198:201], v[98:101]
	v_mfma_f32_16x16x32_bf16 v[106:109], v[170:173], v[194:197], 0
	v_mfma_f32_16x16x32_bf16 v[106:109], v[174:177], v[198:201], v[106:109]
	v_mfma_f32_16x16x32_bf16 v[90:93], v[170:173], v[202:205], 0
	v_mfma_f32_16x16x32_bf16 v[90:93], v[174:177], v[206:209], v[90:93]
	v_mfma_f32_16x16x32_bf16 v[82:85], v[178:181], v[202:205], 0
	v_mfma_f32_16x16x32_bf16 v[82:85], v[182:185], v[206:209], v[82:85]
	s_setprio 2
	s_barrier
	v_mfma_f32_16x16x32_bf16 v[66:69], v[178:181], v[210:213], 0
	v_mfma_f32_16x16x32_bf16 v[66:69], v[182:185], v[214:217], v[66:69]
	v_mfma_f32_16x16x32_bf16 v[74:77], v[170:173], v[210:213], 0
	v_mfma_f32_16x16x32_bf16 v[74:77], v[174:177], v[214:217], v[74:77]
	s_setprio 0
	s_nop 0
	s_add_i32 s45, s35, s26
	s_add_u32 s50, s22, 0x80
	s_addc_u32 s51, s23, 0
	s_add_u32 s52, s24, 0x80
	s_addc_u32 s53, s25, 0
	s_mov_b32 m0, s45
	ds_read_b128 v[186:189], v152 offset:16384
	ds_read_b128 v[190:193], v152 offset:17408
	ds_read_b128 v[194:197], v152 offset:18432
	ds_read_b128 v[198:201], v152 offset:19456
	ds_read_b128 v[202:205], v152 offset:20480
	ds_read_b128 v[206:209], v152 offset:21504
	ds_read_b128 v[210:213], v152 offset:22528
	ds_read_b128 v[214:217], v152 offset:23552
	global_load_lds_dwordx4 v134, s[22:23]
	s_add_i32 m0, s45, 0x2000
	s_add_u32 s46, s22, 0x40000
	s_addc_u32 s47, s23, 0
	s_add_i32 s45, s36, s26
	global_load_lds_dwordx4 v130, s[22:23]
	s_mov_b32 m0, s45
	s_nop 0
	global_load_lds_dwordx4 v134, s[46:47]
	s_add_i32 m0, s45, 0x2000
	s_nop 0
	global_load_lds_dwordx4 v130, s[46:47]
	s_mov_b32 m0, s27
	s_nop 0
	global_load_lds_dwordx4 v136, s[24:25]
	s_mov_b32 m0, s28
	s_nop 0
	global_load_lds_dwordx4 v132, s[24:25]
	s_waitcnt vmcnt(16)
	s_waitcnt lgkmcnt(0)
	s_barrier
	s_setprio 1
	v_mfma_f32_16x16x32_bf16 v[62:65], v[154:157], v[186:189], 0
	v_mfma_f32_16x16x32_bf16 v[62:65], v[158:161], v[190:193], v[62:65]
	v_mfma_f32_16x16x32_bf16 v[54:57], v[162:165], v[186:189], 0
	v_mfma_f32_16x16x32_bf16 v[54:57], v[166:169], v[190:193], v[54:57]
	v_mfma_f32_16x16x32_bf16 v[38:41], v[162:165], v[194:197], 0
	v_mfma_f32_16x16x32_bf16 v[38:41], v[166:169], v[198:201], v[38:41]
	v_mfma_f32_16x16x32_bf16 v[46:49], v[154:157], v[194:197], 0
	v_mfma_f32_16x16x32_bf16 v[46:49], v[158:161], v[198:201], v[46:49]
	v_mfma_f32_16x16x32_bf16 v[30:33], v[154:157], v[202:205], 0
	v_mfma_f32_16x16x32_bf16 v[30:33], v[158:161], v[206:209], v[30:33]
	v_mfma_f32_16x16x32_bf16 v[22:25], v[162:165], v[202:205], 0
	v_mfma_f32_16x16x32_bf16 v[22:25], v[166:169], v[206:209], v[22:25]
	v_mfma_f32_16x16x32_bf16 v[6:9], v[162:165], v[210:213], 0
	v_mfma_f32_16x16x32_bf16 v[6:9], v[166:169], v[214:217], v[6:9]
	v_mfma_f32_16x16x32_bf16 v[14:17], v[154:157], v[210:213], 0
	v_mfma_f32_16x16x32_bf16 v[14:17], v[158:161], v[214:217], v[14:17]
	v_mfma_f32_16x16x32_bf16 v[58:61], v[170:173], v[186:189], 0
	v_mfma_f32_16x16x32_bf16 v[58:61], v[174:177], v[190:193], v[58:61]
	v_mfma_f32_16x16x32_bf16 v[50:53], v[178:181], v[186:189], 0
	v_mfma_f32_16x16x32_bf16 v[50:53], v[182:185], v[190:193], v[50:53]
	v_mfma_f32_16x16x32_bf16 v[34:37], v[178:181], v[194:197], 0
	v_mfma_f32_16x16x32_bf16 v[34:37], v[182:185], v[198:201], v[34:37]
	v_mfma_f32_16x16x32_bf16 v[42:45], v[170:173], v[194:197], 0
	v_mfma_f32_16x16x32_bf16 v[42:45], v[174:177], v[198:201], v[42:45]
	v_mfma_f32_16x16x32_bf16 v[26:29], v[170:173], v[202:205], 0
	v_mfma_f32_16x16x32_bf16 v[26:29], v[174:177], v[206:209], v[26:29]
	v_mfma_f32_16x16x32_bf16 v[18:21], v[178:181], v[202:205], 0
	v_mfma_f32_16x16x32_bf16 v[18:21], v[182:185], v[206:209], v[18:21]
	s_setprio 2
	s_barrier
	v_mfma_f32_16x16x32_bf16 v[2:5], v[178:181], v[210:213], 0
	v_mfma_f32_16x16x32_bf16 v[2:5], v[182:185], v[214:217], v[2:5]
	v_mfma_f32_16x16x32_bf16 v[10:13], v[170:173], v[210:213], 0
	v_mfma_f32_16x16x32_bf16 v[10:13], v[174:177], v[214:217], v[10:13]
	s_setprio 0
	s_nop 0
	s_add_i32 s45, 0, 0x18000
	s_add_i32 s46, 0, 0x1c000
	ds_read_b128 v[154:157], v229 offset:32768
	ds_read_b128 v[158:161], v229 offset:33792
	ds_read_b128 v[162:165], v229 offset:34816
	ds_read_b128 v[166:169], v229 offset:35840
	ds_read_b128 v[170:173], v229 offset:49152
	ds_read_b128 v[174:177], v229 offset:50176
	ds_read_b128 v[178:181], v229 offset:51200
	ds_read_b128 v[182:185], v229 offset:52224
	s_add_u32 s24, s24, 0x40000
	s_addc_u32 s25, s25, 0
	s_mov_b32 m0, s29
	ds_read_b128 v[186:189], v152 offset:32768
	ds_read_b128 v[190:193], v152 offset:33792
	ds_read_b128 v[194:197], v152 offset:34816
	ds_read_b128 v[198:201], v152 offset:35840
	ds_read_b128 v[202:205], v152 offset:36864
	ds_read_b128 v[206:209], v152 offset:37888
	ds_read_b128 v[210:213], v152 offset:38912
	ds_read_b128 v[214:217], v152 offset:39936
	global_load_lds_dwordx4 v136, s[24:25]
	s_mov_b32 m0, s30
	s_nop 0
	global_load_lds_dwordx4 v132, s[24:25]
	s_waitcnt vmcnt(8)
	s_waitcnt lgkmcnt(0)
	s_barrier
	s_setprio 1
	v_mfma_f32_16x16x32_bf16 v[126:129], v[154:157], v[186:189], v[126:129]
	v_mfma_f32_16x16x32_bf16 v[126:129], v[158:161], v[190:193], v[126:129]
	v_mfma_f32_16x16x32_bf16 v[118:121], v[162:165], v[186:189], v[118:121]
	v_mfma_f32_16x16x32_bf16 v[118:121], v[166:169], v[190:193], v[118:121]
	v_mfma_f32_16x16x32_bf16 v[102:105], v[162:165], v[194:197], v[102:105]
	v_mfma_f32_16x16x32_bf16 v[102:105], v[166:169], v[198:201], v[102:105]
	v_mfma_f32_16x16x32_bf16 v[110:113], v[154:157], v[194:197], v[110:113]
	v_mfma_f32_16x16x32_bf16 v[110:113], v[158:161], v[198:201], v[110:113]
	v_mfma_f32_16x16x32_bf16 v[94:97], v[154:157], v[202:205], v[94:97]
	v_mfma_f32_16x16x32_bf16 v[94:97], v[158:161], v[206:209], v[94:97]
	v_mfma_f32_16x16x32_bf16 v[86:89], v[162:165], v[202:205], v[86:89]
	v_mfma_f32_16x16x32_bf16 v[86:89], v[166:169], v[206:209], v[86:89]
	v_mfma_f32_16x16x32_bf16 v[70:73], v[162:165], v[210:213], v[70:73]
	v_mfma_f32_16x16x32_bf16 v[70:73], v[166:169], v[214:217], v[70:73]
	v_mfma_f32_16x16x32_bf16 v[78:81], v[154:157], v[210:213], v[78:81]
	v_mfma_f32_16x16x32_bf16 v[78:81], v[158:161], v[214:217], v[78:81]
	v_mfma_f32_16x16x32_bf16 v[122:125], v[170:173], v[186:189], v[122:125]
	v_mfma_f32_16x16x32_bf16 v[122:125], v[174:177], v[190:193], v[122:125]
	v_mfma_f32_16x16x32_bf16 v[114:117], v[178:181], v[186:189], v[114:117]
	v_mfma_f32_16x16x32_bf16 v[114:117], v[182:185], v[190:193], v[114:117]
	v_mfma_f32_16x16x32_bf16 v[98:101], v[178:181], v[194:197], v[98:101]
	v_mfma_f32_16x16x32_bf16 v[98:101], v[182:185], v[198:201], v[98:101]
	v_mfma_f32_16x16x32_bf16 v[106:109], v[170:173], v[194:197], v[106:109]
	v_mfma_f32_16x16x32_bf16 v[106:109], v[174:177], v[198:201], v[106:109]
	v_mfma_f32_16x16x32_bf16 v[90:93], v[170:173], v[202:205], v[90:93]
	v_mfma_f32_16x16x32_bf16 v[90:93], v[174:177], v[206:209], v[90:93]
	v_mfma_f32_16x16x32_bf16 v[82:85], v[178:181], v[202:205], v[82:85]
	v_mfma_f32_16x16x32_bf16 v[82:85], v[182:185], v[206:209], v[82:85]
	s_setprio 2
	s_barrier
	v_mfma_f32_16x16x32_bf16 v[66:69], v[178:181], v[210:213], v[66:69]
	v_mfma_f32_16x16x32_bf16 v[66:69], v[182:185], v[214:217], v[66:69]
	v_mfma_f32_16x16x32_bf16 v[74:77], v[170:173], v[210:213], v[74:77]
	v_mfma_f32_16x16x32_bf16 v[74:77], v[174:177], v[214:217], v[74:77]
	s_setprio 0
	s_nop 0
	s_add_i32 s24, s45, s26
	s_mov_b32 m0, s24
	ds_read_b128 v[186:189], v152 offset:49152
	ds_read_b128 v[190:193], v152 offset:50176
	ds_read_b128 v[194:197], v152 offset:51200
	ds_read_b128 v[198:201], v152 offset:52224
	ds_read_b128 v[202:205], v152 offset:53248
	ds_read_b128 v[206:209], v152 offset:54272
	ds_read_b128 v[210:213], v152 offset:55296
	ds_read_b128 v[214:217], v152 offset:56320
	global_load_lds_dwordx4 v134, s[50:51]
	s_add_i32 m0, s24, 0x2000
	s_add_u32 s22, s22, 0x40080
	s_addc_u32 s23, s23, 0
	s_add_i32 s24, s46, s26
	global_load_lds_dwordx4 v130, s[50:51]
	s_mov_b32 m0, s24
	s_nop 0
	global_load_lds_dwordx4 v134, s[22:23]
	s_add_i32 m0, s24, 0x2000
	s_nop 0
	global_load_lds_dwordx4 v130, s[22:23]
	s_mov_b32 m0, s33
	s_nop 0
	global_load_lds_dwordx4 v136, s[52:53]
	s_mov_b32 m0, s34
	s_nop 0
	global_load_lds_dwordx4 v132, s[52:53]
	s_waitcnt vmcnt(8)
	s_waitcnt lgkmcnt(0)
	s_barrier
	s_setprio 1
	v_mfma_f32_16x16x32_bf16 v[62:65], v[154:157], v[186:189], v[62:65]
	v_mfma_f32_16x16x32_bf16 v[62:65], v[158:161], v[190:193], v[62:65]
	v_mfma_f32_16x16x32_bf16 v[54:57], v[162:165], v[186:189], v[54:57]
	v_mfma_f32_16x16x32_bf16 v[54:57], v[166:169], v[190:193], v[54:57]
	v_mfma_f32_16x16x32_bf16 v[38:41], v[162:165], v[194:197], v[38:41]
	v_mfma_f32_16x16x32_bf16 v[38:41], v[166:169], v[198:201], v[38:41]
	v_mfma_f32_16x16x32_bf16 v[46:49], v[154:157], v[194:197], v[46:49]
	v_mfma_f32_16x16x32_bf16 v[46:49], v[158:161], v[198:201], v[46:49]
	v_mfma_f32_16x16x32_bf16 v[30:33], v[154:157], v[202:205], v[30:33]
	v_mfma_f32_16x16x32_bf16 v[30:33], v[158:161], v[206:209], v[30:33]
	v_mfma_f32_16x16x32_bf16 v[22:25], v[162:165], v[202:205], v[22:25]
	v_mfma_f32_16x16x32_bf16 v[22:25], v[166:169], v[206:209], v[22:25]
	v_mfma_f32_16x16x32_bf16 v[6:9], v[162:165], v[210:213], v[6:9]
	v_mfma_f32_16x16x32_bf16 v[6:9], v[166:169], v[214:217], v[6:9]
	v_mfma_f32_16x16x32_bf16 v[14:17], v[154:157], v[210:213], v[14:17]
	v_mfma_f32_16x16x32_bf16 v[14:17], v[158:161], v[214:217], v[14:17]
	v_mfma_f32_16x16x32_bf16 v[58:61], v[170:173], v[186:189], v[58:61]
	v_mfma_f32_16x16x32_bf16 v[58:61], v[174:177], v[190:193], v[58:61]
	v_mfma_f32_16x16x32_bf16 v[50:53], v[178:181], v[186:189], v[50:53]
	v_mfma_f32_16x16x32_bf16 v[50:53], v[182:185], v[190:193], v[50:53]
	v_mfma_f32_16x16x32_bf16 v[34:37], v[178:181], v[194:197], v[34:37]
	v_mfma_f32_16x16x32_bf16 v[34:37], v[182:185], v[198:201], v[34:37]
	v_mfma_f32_16x16x32_bf16 v[42:45], v[170:173], v[194:197], v[42:45]
	v_mfma_f32_16x16x32_bf16 v[42:45], v[174:177], v[198:201], v[42:45]
	v_mfma_f32_16x16x32_bf16 v[26:29], v[170:173], v[202:205], v[26:29]
	v_mfma_f32_16x16x32_bf16 v[26:29], v[174:177], v[206:209], v[26:29]
	v_mfma_f32_16x16x32_bf16 v[18:21], v[178:181], v[202:205], v[18:21]
	v_mfma_f32_16x16x32_bf16 v[18:21], v[182:185], v[206:209], v[18:21]
	s_setprio 2
	s_barrier
	v_mfma_f32_16x16x32_bf16 v[2:5], v[178:181], v[210:213], v[2:5]
	v_mfma_f32_16x16x32_bf16 v[2:5], v[182:185], v[214:217], v[2:5]
	v_mfma_f32_16x16x32_bf16 v[10:13], v[170:173], v[210:213], v[10:13]
	v_mfma_f32_16x16x32_bf16 v[10:13], v[174:177], v[214:217], v[10:13]
	s_setprio 0
	s_nop 0
	s_add_i32 s44, s44, 2
	s_add_u32 s20, s20, 0x100
	s_addc_u32 s21, s21, 0
	s_cmp_gt_u32 s44, 13
	s_cbranch_scc1 .LBB0_948
	s_branch .LBB0_946
